# LayerNorm: fp16 residual stores and final f32 output stores marked nt (hb stores stay cached for the next GEMM)
# speedup vs baseline: 1.0059x; 1.0059x over previous
; DI float bf_lo(unsigned u) { return __uint_as_float(u << 16); }
; DI float bf_hi(unsigned u) { return __uint_as_float(u & 0xffff0000u); }
; DI void phase_ln(const Params& p, int layer, int gw, int NGW, int lane) {
;     ...
;             float a1 = 0.f, a2 = 0.f;
; #pragma unroll
;             for (int j = 0; j < 4; ++j) { const unsigned yw[4] = {yv[j].x, yv[j].y, yv[j].z, yv[j].w};
; #pragma unroll
;                 for (int e = 0; e < 4; ++e) { const float u0 = v[q][8 * j + 2 * e] * DN_ALPHA + bf_lo(yw[e]), u1 = v[q][8 * j + 2 * e + 1] * DN_ALPHA + bf_hi(yw[e]);
;                     v[q][8 * j + 2 * e] = u0; v[q][8 * j + 2 * e + 1] = u1; a1 += u0 + u1; a2 += u0 * u0 + u1 * u1; } }
;             s1[q] = a1; s2[q] = a2;
.LBB0_363:
	s_waitcnt vmcnt(7)
	v_lshlrev_b32_e32 v136, 16, v30
	v_and_b32_e32 v137, 0xffff0000, v30
	v_pk_fma_f32 v[144:145], v[50:51], s[98:99], v[136:137] op_sel_hi:[1,0,1]
	v_lshlrev_b32_e32 v30, 16, v31
	v_and_b32_e32 v31, 0xffff0000, v31
	v_lshlrev_b32_e32 v50, 16, v32
	v_and_b32_e32 v51, 0xffff0000, v32
	v_pk_fma_f32 v[148:149], v[52:53], s[98:99], v[30:31] op_sel_hi:[1,0,1]
	v_pk_fma_f32 v[146:147], v[42:43], s[98:99], v[50:51] op_sel_hi:[1,0,1]
	s_waitcnt vmcnt(6)
	v_lshlrev_b32_e32 v50, 16, v12
	v_and_b32_e32 v51, 0xffff0000, v12
	v_pk_add_f32 v[162:163], v[144:145], v[144:145] op_sel_hi:[1,0]
	v_pk_mul_f32 v[164:165], v[144:145], v[144:145]
	v_pk_mul_f32 v[30:31], v[148:149], v[148:149]
	v_lshlrev_b32_e32 v32, 16, v33
	v_and_b32_e32 v33, 0xffff0000, v33
	v_pk_fma_f32 v[140:141], v[46:47], s[98:99], v[50:51] op_sel_hi:[1,0,1]
	s_waitcnt vmcnt(5)
	v_lshlrev_b32_e32 v46, 16, v6
	v_and_b32_e32 v47, 0xffff0000, v6
	v_pk_fma_f32 v[150:151], v[44:45], s[98:99], v[32:33] op_sel_hi:[1,0,1]
	v_lshlrev_b32_e32 v44, 16, v10
	v_and_b32_e32 v45, 0xffff0000, v10
	v_lshlrev_b32_e32 v10, 16, v11
	v_and_b32_e32 v11, 0xffff0000, v11
	v_pk_fma_f32 v[46:47], v[58:59], s[98:99], v[46:47] op_sel_hi:[1,0,1]
	v_mov_b32_e32 v162, v164
	v_mov_b32_e32 v0, v165
	v_mov_b32_e32 v58, v31
	v_mov_b32_e32 v59, v149
	v_mov_b32_e32 v31, v148
	v_pk_mul_f32 v[42:43], v[146:147], v[146:147]
	v_pk_fma_f32 v[138:139], v[56:57], s[98:99], v[10:11] op_sel_hi:[1,0,1]
	v_pk_add_f32 v[56:57], v[162:163], v[0:1]
	v_pk_add_f32 v[30:31], v[58:59], v[30:31]
	v_pk_mul_f32 v[32:33], v[150:151], v[150:151]
	v_pk_add_f32 v[30:31], v[30:31], v[56:57]
	v_mov_b32_e32 v56, v43
	v_mov_b32_e32 v57, v147
	v_mov_b32_e32 v43, v146
	v_pk_add_f32 v[42:43], v[56:57], v[42:43]
	v_pk_fma_f32 v[136:137], v[54:55], s[98:99], v[44:45] op_sel_hi:[1,0,1]
	v_pk_add_f32 v[30:31], v[42:43], v[30:31]
	v_mov_b32_e32 v42, v33
	v_mov_b32_e32 v43, v151
	v_mov_b32_e32 v33, v150
	v_pk_mul_f32 v[44:45], v[136:137], v[136:137]
	v_pk_add_f32 v[32:33], v[42:43], v[32:33]
	v_pk_mul_f32 v[10:11], v[138:139], v[138:139]
	v_pk_add_f32 v[30:31], v[32:33], v[30:31]
	v_mov_b32_e32 v32, v45
	v_mov_b32_e32 v33, v137
	v_mov_b32_e32 v45, v136
	v_pk_add_f32 v[32:33], v[32:33], v[44:45]
	v_pk_mul_f32 v[52:53], v[140:141], v[140:141]
	v_pk_add_f32 v[30:31], v[32:33], v[30:31]
	v_mov_b32_e32 v32, v11
	v_mov_b32_e32 v33, v139
	v_mov_b32_e32 v11, v138
	v_lshlrev_b32_e32 v12, 16, v13
	v_and_b32_e32 v13, 0xffff0000, v13
	v_pk_add_f32 v[10:11], v[32:33], v[10:11]
	v_pk_fma_f32 v[142:143], v[48:49], s[98:99], v[12:13] op_sel_hi:[1,0,1]
	v_pk_add_f32 v[10:11], v[10:11], v[30:31]
	v_mov_b32_e32 v30, v53
	v_mov_b32_e32 v31, v141
	v_mov_b32_e32 v53, v140
	v_pk_mul_f32 v[12:13], v[142:143], v[142:143]
	v_pk_add_f32 v[30:31], v[30:31], v[52:53]
	v_pk_mul_f32 v[54:55], v[46:47], v[46:47]
	v_pk_add_f32 v[10:11], v[30:31], v[10:11]
	v_mov_b32_e32 v30, v13
	v_mov_b32_e32 v31, v143
	v_mov_b32_e32 v13, v142
	v_lshlrev_b32_e32 v6, 16, v7
	v_and_b32_e32 v7, 0xffff0000, v7
	v_pk_add_f32 v[12:13], v[30:31], v[12:13]
	v_pk_fma_f32 v[50:51], v[60:61], s[98:99], v[6:7] op_sel_hi:[1,0,1]
	v_pk_add_f32 v[10:11], v[12:13], v[10:11]
	v_mov_b32_e32 v12, v55
	v_mov_b32_e32 v13, v47
	v_mov_b32_e32 v55, v46
	v_pk_mul_f32 v[6:7], v[50:51], v[50:51]
	v_lshlrev_b32_e32 v48, 16, v8
	v_and_b32_e32 v49, 0xffff0000, v8
	v_pk_add_f32 v[12:13], v[12:13], v[54:55]
	v_pk_fma_f32 v[48:49], v[22:23], s[98:99], v[48:49] op_sel_hi:[1,0,1]
	v_pk_add_f32 v[10:11], v[12:13], v[10:11]
	v_mov_b32_e32 v12, v7
	v_mov_b32_e32 v13, v51
	v_mov_b32_e32 v7, v50
	v_pk_mul_f32 v[22:23], v[48:49], v[48:49]
	v_pk_add_f32 v[6:7], v[12:13], v[6:7]
	v_lshlrev_b32_e32 v8, 16, v9
	v_and_b32_e32 v9, 0xffff0000, v9
	v_pk_add_f32 v[6:7], v[6:7], v[10:11]
	v_mov_b32_e32 v10, v23
	v_mov_b32_e32 v11, v49
	v_mov_b32_e32 v23, v48
	v_pk_fma_f32 v[52:53], v[24:25], s[98:99], v[8:9] op_sel_hi:[1,0,1]
	v_pk_add_f32 v[10:11], v[10:11], v[22:23]
	v_pk_mul_f32 v[8:9], v[52:53], v[52:53]
	v_pk_add_f32 v[6:7], v[10:11], v[6:7]
	v_mov_b32_e32 v10, v9
	v_mov_b32_e32 v11, v53
	v_mov_b32_e32 v9, v52
	v_pk_add_f32 v[8:9], v[10:11], v[8:9]
	s_waitcnt vmcnt(4)
	v_lshlrev_b32_e32 v10, 16, v2
	v_and_b32_e32 v11, 0xffff0000, v2
	v_pk_fma_f32 v[30:31], v[14:15], s[98:99], v[10:11] op_sel_hi:[1,0,1]
	v_lshlrev_b32_e32 v2, 16, v3
	v_pk_mul_f32 v[10:11], v[30:31], v[30:31]
	v_and_b32_e32 v3, 0xffff0000, v3
	v_pk_fma_f32 v[42:43], v[16:17], s[98:99], v[2:3] op_sel_hi:[1,0,1]
	v_pk_add_f32 v[6:7], v[8:9], v[6:7]
	v_mov_b32_e32 v8, v11
	v_mov_b32_e32 v9, v31
	v_mov_b32_e32 v11, v30
	v_pk_mul_f32 v[2:3], v[42:43], v[42:43]
	v_lshlrev_b32_e32 v12, 16, v4
	v_and_b32_e32 v13, 0xffff0000, v4
	v_pk_add_f32 v[8:9], v[8:9], v[10:11]
	v_pk_fma_f32 v[32:33], v[18:19], s[98:99], v[12:13] op_sel_hi:[1,0,1]
	v_pk_add_f32 v[6:7], v[8:9], v[6:7]
	v_mov_b32_e32 v8, v3
	v_mov_b32_e32 v9, v43
	v_mov_b32_e32 v3, v42
	v_pk_mul_f32 v[12:13], v[32:33], v[32:33]
	v_lshlrev_b32_e32 v4, 16, v5
	v_and_b32_e32 v5, 0xffff0000, v5
	v_pk_add_f32 v[2:3], v[8:9], v[2:3]
	v_pk_fma_f32 v[44:45], v[20:21], s[98:99], v[4:5] op_sel_hi:[1,0,1]
	v_pk_add_f32 v[2:3], v[2:3], v[6:7]
	v_mov_b32_e32 v6, v13
	v_mov_b32_e32 v7, v33
	v_mov_b32_e32 v13, v32
	v_pk_mul_f32 v[4:5], v[44:45], v[44:45]
	v_pk_add_f32 v[6:7], v[6:7], v[12:13]
	s_waitcnt vmcnt(3)
; DI float bf_lo(unsigned u) { return __uint_as_float(u << 16); }
; DI float bf_hi(unsigned u) { return __uint_as_float(u & 0xffff0000u); }
; DI float shflx(float v, int mask, int lane) { return __int_as_float(__builtin_amdgcn_ds_bpermute((lane ^ mask) << 2, __float_as_int(v))); }
; DI void phase_ln(const Params& p, int layer, int gw, int NGW, int lane) {
;     ...
;             for (int j = 0; j < 4; ++j) { const unsigned yw[4] = {yv[j].x, yv[j].y, yv[j].z, yv[j].w};
; #pragma unroll
;                 for (int e = 0; e < 4; ++e) { const float u0 = v[q][8 * j + 2 * e] * DN_ALPHA + bf_lo(yw[e]), u1 = v[q][8 * j + 2 * e + 1] * DN_ALPHA + bf_hi(yw[e]);
;                     v[q][8 * j + 2 * e] = u0; v[q][8 * j + 2 * e + 1] = u1; a1 += u0 + u1; a2 += u0 * u0 + u1 * u1; } }
;             s1[q] = a1; s2[q] = a2;
;         }
; #pragma unroll
;         for (int o = 1; o < 64; o <<= 1)
; #pragma unroll
;             for (int q = 0; q < R; ++q) { s1[q] += shflx(s1[q], o, lane); s2[q] += shflx(s2[q], o, lane); }
	v_lshlrev_b32_e32 v8, 16, v65
	v_pk_add_f32 v[2:3], v[6:7], v[2:3]
	v_mov_b32_e32 v6, v5
	v_mov_b32_e32 v7, v45
	v_mov_b32_e32 v5, v44
	v_pk_add_f32 v[4:5], v[6:7], v[4:5]
	v_lshlrev_b32_e32 v6, 16, v64
	v_pk_add_f32 v[18:19], v[4:5], v[2:3]
	v_lshlrev_b32_e32 v2, 16, v62
	v_and_b32_e32 v3, 0xffff0000, v62
	v_pk_fma_f32 v[94:95], v[94:95], s[98:99], v[2:3] op_sel_hi:[1,0,1]
	v_lshlrev_b32_e32 v4, 16, v63
	v_and_b32_e32 v5, 0xffff0000, v63
	v_add_f32_e32 v0, v95, v94
	v_pk_fma_f32 v[96:97], v[96:97], s[98:99], v[4:5] op_sel_hi:[1,0,1]
	v_and_b32_e32 v7, 0xffff0000, v64
	v_add_f32_e32 v0, 0, v0
	v_add_f32_e32 v4, v97, v96
	v_pk_fma_f32 v[82:83], v[82:83], s[98:99], v[6:7] op_sel_hi:[1,0,1]
	v_and_b32_e32 v9, 0xffff0000, v65
	v_add_f32_e32 v0, v4, v0
	v_add_f32_e32 v6, v83, v82
	v_pk_fma_f32 v[84:85], v[84:85], s[98:99], v[8:9] op_sel_hi:[1,0,1]
	s_waitcnt vmcnt(2)
	v_lshlrev_b32_e32 v10, 16, v38
	v_and_b32_e32 v11, 0xffff0000, v38
	v_pk_mul_f32 v[2:3], v[94:95], v[94:95]
	v_pk_mul_f32 v[4:5], v[96:97], v[96:97]
	v_add_f32_e32 v0, v6, v0
	v_add_f32_e32 v8, v85, v84
	v_pk_fma_f32 v[58:59], v[90:91], s[98:99], v[10:11] op_sel_hi:[1,0,1]
	v_lshlrev_b32_e32 v12, 16, v39
	v_and_b32_e32 v13, 0xffff0000, v39
	v_pk_mul_f32 v[6:7], v[82:83], v[82:83]
	v_add_f32_e32 v0, v8, v0
	v_add_f32_e32 v10, v59, v58
	v_pk_fma_f32 v[62:63], v[92:93], s[98:99], v[12:13] op_sel_hi:[1,0,1]
	v_lshlrev_b32_e32 v14, 16, v40
	v_and_b32_e32 v15, 0xffff0000, v40
	v_add_f32_e32 v4, v5, v4
	v_add_f32_e32 v2, v3, v2
	v_pk_mul_f32 v[8:9], v[84:85], v[84:85]
	v_add_f32_e32 v0, v10, v0
	v_add_f32_e32 v12, v63, v62
	v_pk_fma_f32 v[64:65], v[70:71], s[98:99], v[14:15] op_sel_hi:[1,0,1]
	v_lshlrev_b32_e32 v16, 16, v41
	v_and_b32_e32 v17, 0xffff0000, v41
	v_add_f32_e32 v2, v4, v2
	v_add_f32_e32 v3, v7, v6
	v_pk_mul_f32 v[10:11], v[58:59], v[58:59]
	v_add_f32_e32 v0, v12, v0
	v_add_f32_e32 v14, v65, v64
	v_pk_fma_f32 v[70:71], v[72:73], s[98:99], v[16:17] op_sel_hi:[1,0,1]
	s_waitcnt vmcnt(1)
	v_lshlrev_b32_e32 v20, 16, v34
	v_and_b32_e32 v21, 0xffff0000, v34
	v_add_f32_e32 v8, v9, v8
	v_add_f32_e32 v2, v3, v2
	v_pk_mul_f32 v[12:13], v[62:63], v[62:63]
	v_add_f32_e32 v0, v14, v0
	v_add_f32_e32 v16, v71, v70
	v_pk_fma_f32 v[38:39], v[86:87], s[98:99], v[20:21] op_sel_hi:[1,0,1]
	v_lshlrev_b32_e32 v22, 16, v35
	v_and_b32_e32 v23, 0xffff0000, v35
	v_add_f32_e32 v2, v8, v2
	v_add_f32_e32 v3, v11, v10
	v_pk_mul_f32 v[14:15], v[64:65], v[64:65]
	v_add_f32_e32 v0, v16, v0
	v_add_f32_e32 v20, v39, v38
	v_pk_fma_f32 v[40:41], v[88:89], s[98:99], v[22:23] op_sel_hi:[1,0,1]
	v_lshlrev_b32_e32 v24, 16, v36
	v_and_b32_e32 v25, 0xffff0000, v36
	v_add_f32_e32 v2, v3, v2
	v_add_f32_e32 v3, v13, v12
	v_pk_mul_f32 v[16:17], v[70:71], v[70:71]
	v_add_f32_e32 v0, v20, v0
	v_add_f32_e32 v22, v41, v40
	v_pk_fma_f32 v[54:55], v[78:79], s[98:99], v[24:25] op_sel_hi:[1,0,1]
	v_lshlrev_b32_e32 v34, 16, v37
	v_and_b32_e32 v35, 0xffff0000, v37
	v_add_f32_e32 v2, v3, v2
	v_add_f32_e32 v3, v15, v14
	v_pk_mul_f32 v[20:21], v[38:39], v[38:39]
	v_add_f32_e32 v0, v22, v0
	v_add_f32_e32 v24, v55, v54
	v_pk_fma_f32 v[56:57], v[80:81], s[98:99], v[34:35] op_sel_hi:[1,0,1]
	v_add_f32_e32 v2, v3, v2
	v_add_f32_e32 v3, v17, v16
	v_pk_mul_f32 v[22:23], v[40:41], v[40:41]
	v_add_f32_e32 v0, v24, v0
	v_add_f32_e32 v34, v57, v56
	v_add_f32_e32 v2, v3, v2
	v_add_f32_e32 v3, v21, v20
	v_pk_mul_f32 v[24:25], v[54:55], v[54:55]
	v_add_f32_e32 v0, v34, v0
	s_waitcnt vmcnt(0)
	v_lshlrev_b32_e32 v34, 16, v26
	v_and_b32_e32 v35, 0xffff0000, v26
	v_add_f32_e32 v2, v3, v2
	v_add_f32_e32 v3, v23, v22
	v_pk_mul_f32 v[60:61], v[56:57], v[56:57]
	v_pk_fma_f32 v[34:35], v[74:75], s[98:99], v[34:35] op_sel_hi:[1,0,1]
	v_add_f32_e32 v2, v3, v2
	v_add_f32_e32 v3, v25, v24
	v_pk_mul_f32 v[72:73], v[34:35], v[34:35]
	v_add_f32_e32 v2, v3, v2
	v_add_f32_e32 v3, v61, v60
	v_add_f32_e32 v2, v3, v2
	v_add_f32_e32 v3, v73, v72
	v_add_f32_e32 v22, v3, v2
	global_load_dwordx4 v[2:5], v[108:109], off offset:16
	global_load_dwordx4 v[10:13], v[108:109], off
	global_load_dwordx4 v[6:9], v[110:111], off offset:16
	global_load_dwordx4 v[14:17], v[110:111], off
	ds_bpermute_b32 v21, v152, v19
	ds_bpermute_b32 v20, v152, v18
	v_add_f32_e32 v26, v35, v34
	v_add_f32_e32 v0, v26, v0
	v_lshlrev_b32_e32 v26, 16, v27
	v_and_b32_e32 v27, 0xffff0000, v27
	s_waitcnt lgkmcnt(0)
	v_pk_add_f32 v[18:19], v[18:19], v[20:21]
	ds_bpermute_b32 v21, v153, v19
	ds_bpermute_b32 v20, v153, v18
	v_pk_fma_f32 v[26:27], v[76:77], s[98:99], v[26:27] op_sel_hi:[1,0,1]
	v_and_b32_e32 v37, 0xffff0000, v28
	v_add_f32_e32 v36, v27, v26
	v_add_f32_e32 v0, v36, v0
	s_waitcnt lgkmcnt(0)
	v_pk_add_f32 v[18:19], v[18:19], v[20:21]
	ds_bpermute_b32 v21, v158, v19
	ds_bpermute_b32 v20, v158, v18
	v_lshlrev_b32_e32 v36, 16, v28
	v_pk_fma_f32 v[36:37], v[66:67], s[98:99], v[36:37] op_sel_hi:[1,0,1]
	v_pk_mul_f32 v[74:75], v[26:27], v[26:27]
	v_add_f32_e32 v28, v36, v37
	v_add_f32_e32 v0, v28, v0
	v_lshlrev_b32_e32 v28, 16, v29
	v_and_b32_e32 v29, 0xffff0000, v29
	s_waitcnt lgkmcnt(0)
	v_pk_add_f32 v[18:19], v[18:19], v[20:21]
	v_pk_fma_f32 v[28:29], v[68:69], s[98:99], v[28:29] op_sel_hi:[1,0,1]
	ds_bpermute_b32 v21, v159, v19
	ds_bpermute_b32 v20, v159, v18
	v_pk_mul_f32 v[66:67], v[36:37], v[36:37]
	v_add_f32_e32 v68, v28, v29
	v_add_f32_e32 v23, v75, v74
	v_add_f32_e32 v0, v68, v0
	v_pk_mul_f32 v[68:69], v[28:29], v[28:29]
	v_add_f32_e32 v22, v23, v22
	v_add_f32_e32 v23, v66, v67
	v_add_f32_e32 v22, v23, v22
	v_add_f32_e32 v23, v68, v69
	v_add_f32_e32 v22, v23, v22
	ds_bpermute_b32 v23, v152, v22
	s_waitcnt lgkmcnt(1)
; DI unsigned pk2(float a, float b) { f32x2 v = {a, b}; bf16v2 r = __builtin_convertvector(v, bf16v2); return __builtin_bit_cast(unsigned, r); }
; DI unsigned pkh2(float a, float b) { f32x2 v = {a, b}; h16v2 r = __builtin_convertvector(v, h16v2); return __builtin_bit_cast(unsigned, r); }
; DI void phase_ln(const Params& p, int layer, int gw, int NGW, int lane) {
;     ...
;         float mean[R], rstd[R];
; #pragma unroll
;         for (int q = 0; q < R; ++q) { mean[q] = s1[q] * (1.f / D); const float var = fmaxf(s2[q] * (1.f / D) - mean[q] * mean[q], 0.f); rstd[q] = 1.0f / sqrtf(var + LN_EPS); }
; #pragma unroll
;         for (int j = 0; j < 4; ++j) {
;             const f32x4 g0 = ((const f32x4*)g)[128 * j + 2 * lane], g1 = ((const f32x4*)g)[128 * j + 2 * lane + 1], b0 = ((const f32x4*)b)[128 * j + 2 * lane], b1 = ((const f32x4*)b)[128 * j + 2 * lane + 1];
;             const float gg[8] = {g0[0], g0[1], g0[2], g0[3], g1[0], g1[1], g1[2], g1[3]}, bb[8] = {b0[0], b0[1], b0[2], b0[3], b1[0], b1[1], b1[2], b1[3]};
; #pragma unroll
;             for (int q = 0; q < R; ++q) { if (!ok[q]) continue;
;                 float y[8];
; #pragma unroll
;                 for (int e = 0; e < 8; ++e) y[e] = (v[q][8 * j + e] - mean[q]) * rstd[q] * gg[e] + bb[e];
;                 if (last) { f32x4* o = (f32x4*)(p.out + (size_t)rr[q] * D) + 128 * j + 2 * lane; o[0] = (f32x4){y[0], y[1], y[2], y[3]}; o[1] = (f32x4){y[4], y[5], y[6], y[7]}; }
;                 else { u32x4 hw; hw.x = pkh2(y[0], y[1]); hw.y = pkh2(y[2], y[3]); hw.z = pkh2(y[4], y[5]); hw.w = pkh2(y[6], y[7]);
;                        ((u32x4*)(h16out + (size_t)rr[q] * D) + lane)[64 * j] = hw;
;                        u32x4 w; w.x = pk2(y[0], y[1]); w.y = pk2(y[2], y[3]); w.z = pk2(y[4], y[5]); w.w = pk2(y[6], y[7]);
;                        ((u32x4*)(hb + (size_t)rr[q] * D) + lane)[64 * j] = w; } }
	v_pk_add_f32 v[18:19], v[18:19], v[20:21]
	ds_bpermute_b32 v21, v160, v19
	ds_bpermute_b32 v20, v160, v18
	ds_bpermute_b32 v24, v152, v0
	s_waitcnt lgkmcnt(3)
	v_add_f32_e32 v22, v22, v23
	ds_bpermute_b32 v23, v153, v22
	v_lshl_add_u64 v[68:69], s[52:53], 0, v[98:99]
	s_waitcnt lgkmcnt(2)
	v_pk_add_f32 v[18:19], v[18:19], v[20:21]
	ds_bpermute_b32 v21, v161, v19
	ds_bpermute_b32 v20, v161, v18
	s_waitcnt lgkmcnt(2)
	v_add_f32_e32 v22, v22, v23
	ds_bpermute_b32 v23, v158, v22
	v_add_f32_e32 v0, v0, v24
	ds_bpermute_b32 v24, v153, v0
	s_waitcnt lgkmcnt(2)
	v_pk_add_f32 v[18:19], v[18:19], v[20:21]
	s_waitcnt lgkmcnt(1)
	v_add_f32_e32 v22, v22, v23
	v_pk_mul_f32 v[60:61], v[18:19], s[2:3] op_sel_hi:[1,0]
	ds_bpermute_b32 v23, v159, v22
	v_fma_f32 v18, -v61, v61, v60
	v_max_f32_e32 v18, 0, v18
	v_add_f32_e32 v18, 0x3727c5ac, v18
	v_mul_f32_e32 v19, 0x4f800000, v18
	v_cmp_gt_f32_e32 vcc, s19, v18
	s_waitcnt lgkmcnt(1)
	v_add_f32_e32 v0, v0, v24
	s_waitcnt lgkmcnt(0)
	v_add_f32_e32 v20, v22, v23
	v_cndmask_b32_e32 v18, v18, v19, vcc
	v_sqrt_f32_e32 v19, v18
	ds_bpermute_b32 v24, v158, v0
	ds_bpermute_b32 v21, v160, v20
	v_add_u32_e32 v22, -1, v19
	v_fma_f32 v23, -v22, v19, v18
	v_cmp_ge_f32_e64 s[36:37], 0, v23
	v_add_u32_e32 v23, 1, v19
	s_waitcnt lgkmcnt(1)
	v_add_f32_e32 v0, v0, v24
	v_cndmask_b32_e64 v22, v19, v22, s[36:37]
	v_fma_f32 v19, -v23, v19, v18
	v_cmp_lt_f32_e64 s[36:37], 0, v19
	ds_bpermute_b32 v24, v159, v0
	s_waitcnt lgkmcnt(1)
	v_add_f32_e32 v67, v20, v21
	v_cndmask_b32_e64 v19, v22, v23, s[36:37]
	v_mul_f32_e32 v22, 0x37800000, v19
	v_cndmask_b32_e32 v19, v19, v22, vcc
	v_cmp_class_f32_e32 vcc, v18, v174
	s_waitcnt lgkmcnt(0)
	v_add_f32_e32 v0, v0, v24
	ds_bpermute_b32 v24, v160, v0
	v_cndmask_b32_e32 v18, v19, v18, vcc
	v_div_scale_f32 v19, s[6:7], v18, v18, 1.0
	v_rcp_f32_e32 v22, v19
	s_waitcnt lgkmcnt(0)
	v_add_f32_e32 v0, v0, v24
	ds_bpermute_b32 v72, v161, v0
	ds_bpermute_b32 v73, v161, v67
	v_fma_f32 v20, -v19, v22, 1.0
	v_fmac_f32_e32 v22, v20, v22
	v_div_scale_f32 v20, vcc, 1.0, v18, 1.0
	v_mul_f32_e32 v21, v20, v22
	v_fma_f32 v23, -v19, v21, v20
	v_fmac_f32_e32 v21, v23, v22
	v_fma_f32 v19, -v19, v21, v20
	v_div_fmas_f32 v19, v19, v22, v21
	v_div_fixup_f32 v66, v19, v18, 1.0
	v_pk_add_f32 v[18:19], v[144:145], v[60:61] op_sel:[0,1] neg_lo:[0,1] neg_hi:[0,1]
	v_pk_add_f32 v[20:21], v[148:149], v[60:61] op_sel:[0,1] neg_lo:[0,1] neg_hi:[0,1]
	v_pk_add_f32 v[22:23], v[146:147], v[60:61] op_sel:[0,1] neg_lo:[0,1] neg_hi:[0,1]
	v_pk_add_f32 v[24:25], v[150:151], v[60:61] op_sel:[0,1] neg_lo:[0,1] neg_hi:[0,1]
	v_pk_mul_f32 v[18:19], v[18:19], v[66:67] op_sel_hi:[1,0]
	v_pk_mul_f32 v[20:21], v[20:21], v[66:67] op_sel_hi:[1,0]
	v_pk_mul_f32 v[22:23], v[22:23], v[66:67] op_sel_hi:[1,0]
	v_pk_mul_f32 v[24:25], v[24:25], v[66:67] op_sel_hi:[1,0]
	s_waitcnt vmcnt(0)
	v_pk_fma_f32 v[18:19], v[10:11], v[18:19], v[14:15]
	v_pk_fma_f32 v[20:21], v[12:13], v[20:21], v[16:17]
	v_pk_fma_f32 v[22:23], v[2:3], v[22:23], v[6:7]
	v_pk_fma_f32 v[24:25], v[4:5], v[24:25], v[8:9]
	s_mov_b64 s[6:7], -1
	s_and_b64 vcc, exec, s[0:1]
	s_cbranch_vccz .LBB0_365
	s_mov_b64 s[6:7], 0x8400000
	v_cvt_pk_f16_f32 v74, v18, v19
	v_cvt_pk_f16_f32 v75, v20, v21
	v_cvt_pk_f16_f32 v76, v22, v23
	v_cvt_pk_f16_f32 v77, v24, v25
	v_lshl_add_u64 v[78:79], v[132:133], 0, s[6:7]
	global_store_dwordx4 v[68:69], v[74:77], off nt
	s_mov_b64 s[6:7], 0
	s_nop 0
	v_cvt_pk_bf16_f32 v74, v18, v19
	v_cvt_pk_bf16_f32 v75, v20, v21
	v_cvt_pk_bf16_f32 v76, v22, v23
	v_cvt_pk_bf16_f32 v77, v24, v25
	global_store_dwordx4 v[78:79], v[74:77], off
.LBB0_365:
	s_andn2_b64 vcc, exec, s[6:7]
	s_cbranch_vccnz .LBB0_367
	global_store_dwordx4 v[130:131], v[18:21], off offset:-4096 nt
	global_store_dwordx4 v[130:131], v[22:25], off offset:-4080 nt
.LBB0_367:
	s_waitcnt lgkmcnt(1)
	v_add_f32_e32 v0, v0, v72
	v_mul_f32_e32 v0, 0x3a000000, v0
	s_waitcnt lgkmcnt(0)
	v_add_f32_e32 v18, v67, v73
	v_mul_f32_e32 v19, v0, v0
	v_fma_f32 v18, v18, s2, -v19
	v_max_f32_e32 v18, 0, v18
	v_add_f32_e32 v18, 0x3727c5ac, v18
	v_mul_f32_e32 v19, 0x4f800000, v18
	v_cmp_gt_f32_e32 vcc, s19, v18
	s_nop 1
	v_cndmask_b32_e32 v18, v18, v19, vcc
	v_sqrt_f32_e32 v19, v18
	s_nop 0
	v_add_u32_e32 v20, -1, v19
	v_fma_f32 v21, -v20, v19, v18
	v_cmp_ge_f32_e64 s[36:37], 0, v21
	v_add_u32_e32 v21, 1, v19
	s_nop 0
	v_cndmask_b32_e64 v20, v19, v20, s[36:37]
	v_fma_f32 v19, -v21, v19, v18
	v_cmp_lt_f32_e64 s[36:37], 0, v19
	s_nop 1
	v_cndmask_b32_e64 v19, v20, v21, s[36:37]
	v_mul_f32_e32 v20, 0x37800000, v19
	v_cndmask_b32_e32 v19, v19, v20, vcc
	v_cmp_class_f32_e32 vcc, v18, v174
	s_nop 1
	v_cndmask_b32_e32 v18, v19, v18, vcc
	v_div_scale_f32 v19, s[6:7], v18, v18, 1.0
	v_rcp_f32_e32 v20, v19
	s_nop 0
	v_fma_f32 v21, -v19, v20, 1.0
	v_fmac_f32_e32 v20, v21, v20
	v_div_scale_f32 v21, vcc, 1.0, v18, 1.0
	v_mul_f32_e32 v22, v21, v20
	v_fma_f32 v23, -v19, v22, v21
	v_fmac_f32_e32 v22, v23, v20
	v_fma_f32 v19, -v19, v22, v21
	v_div_fmas_f32 v19, v19, v20, v22
	v_cndmask_b32_e64 v20, 0, 1, s[4:5]
	v_cmp_ne_u32_e64 s[36:37], 1, v20
	s_andn2_b64 vcc, exec, s[4:5]
	v_div_fixup_f32 v72, v19, v18, 1.0
	s_cbranch_vccnz .LBB0_372
	v_pk_add_f32 v[18:19], v[94:95], v[0:1] op_sel_hi:[1,0] neg_lo:[0,1] neg_hi:[0,1]
	s_andn2_b64 vcc, exec, s[0:1]
	v_pk_mul_f32 v[18:19], v[18:19], v[72:73] op_sel_hi:[1,0]
	s_mov_b64 s[4:5], -1
	v_pk_fma_f32 v[10:11], v[10:11], v[18:19], v[14:15]
	v_pk_add_f32 v[14:15], v[96:97], v[0:1] op_sel_hi:[1,0] neg_lo:[0,1] neg_hi:[0,1]
	s_nop 0
	v_pk_mul_f32 v[14:15], v[14:15], v[72:73] op_sel_hi:[1,0]
	s_nop 0
	v_pk_fma_f32 v[12:13], v[12:13], v[14:15], v[16:17]
	v_pk_add_f32 v[14:15], v[82:83], v[0:1] op_sel_hi:[1,0] neg_lo:[0,1] neg_hi:[0,1]
	s_nop 0
	v_pk_mul_f32 v[14:15], v[14:15], v[72:73] op_sel_hi:[1,0]
	s_nop 0
	v_pk_fma_f32 v[2:3], v[2:3], v[14:15], v[6:7]
	v_pk_add_f32 v[6:7], v[84:85], v[0:1] op_sel_hi:[1,0] neg_lo:[0,1] neg_hi:[0,1]
	s_nop 0
	v_pk_mul_f32 v[6:7], v[6:7], v[72:73] op_sel_hi:[1,0]
	s_nop 0
	v_pk_fma_f32 v[4:5], v[4:5], v[6:7], v[8:9]
	s_cbranch_vccnz .LBB0_370
	v_cvt_pk_f16_f32 v6, v10, v11
	v_cvt_pk_f16_f32 v7, v12, v13
	v_cvt_pk_f16_f32 v8, v2, v3
	v_cvt_pk_f16_f32 v9, v4, v5
	v_lshl_add_u64 v[14:15], v[106:107], 0, s[58:59]
	global_store_dwordx4 v[14:15], v[6:9], off nt
	s_mov_b64 s[4:5], 0
	s_nop 0
	v_cvt_pk_bf16_f32 v6, v10, v11
	v_cvt_pk_bf16_f32 v7, v12, v13
	v_cvt_pk_bf16_f32 v8, v2, v3
	v_cvt_pk_bf16_f32 v9, v4, v5
	global_store_dwordx4 v[134:135], v[6:9], off
.LBB0_370:
	s_andn2_b64 vcc, exec, s[4:5]
	s_cbranch_vccnz .LBB0_372
	s_lshl_b64 s[4:5], s[56:57], 13
	v_lshl_add_u64 v[6:7], v[128:129], 0, s[4:5]
	global_store_dwordx4 v[6:7], v[10:13], off nt
	global_store_dwordx4 v[6:7], v[2:5], off offset:16 nt

; DI unsigned pk2(float a, float b) { f32x2 v = {a, b}; bf16v2 r = __builtin_convertvector(v, bf16v2); return __builtin_bit_cast(unsigned, r); }
; DI unsigned pkh2(float a, float b) { f32x2 v = {a, b}; h16v2 r = __builtin_convertvector(v, h16v2); return __builtin_bit_cast(unsigned, r); }
; DI void phase_ln(const Params& p, int layer, int gw, int NGW, int lane) {
;     ...
;         for (int j = 0; j < 4; ++j) {
;             const f32x4 g0 = ((const f32x4*)g)[128 * j + 2 * lane], g1 = ((const f32x4*)g)[128 * j + 2 * lane + 1], b0 = ((const f32x4*)b)[128 * j + 2 * lane], b1 = ((const f32x4*)b)[128 * j + 2 * lane + 1];
;             const float gg[8] = {g0[0], g0[1], g0[2], g0[3], g1[0], g1[1], g1[2], g1[3]}, bb[8] = {b0[0], b0[1], b0[2], b0[3], b1[0], b1[1], b1[2], b1[3]};
; #pragma unroll
;             for (int q = 0; q < R; ++q) { if (!ok[q]) continue;
;                 float y[8];
; #pragma unroll
;                 for (int e = 0; e < 8; ++e) y[e] = (v[q][8 * j + e] - mean[q]) * rstd[q] * gg[e] + bb[e];
;                 if (last) { f32x4* o = (f32x4*)(p.out + (size_t)rr[q] * D) + 128 * j + 2 * lane; o[0] = (f32x4){y[0], y[1], y[2], y[3]}; o[1] = (f32x4){y[4], y[5], y[6], y[7]}; }
;                 else { u32x4 hw; hw.x = pkh2(y[0], y[1]); hw.y = pkh2(y[2], y[3]); hw.z = pkh2(y[4], y[5]); hw.w = pkh2(y[6], y[7]);
;                        ((u32x4*)(h16out + (size_t)rr[q] * D) + lane)[64 * j] = hw;
;                        u32x4 w; w.x = pk2(y[0], y[1]); w.y = pk2(y[2], y[3]); w.z = pk2(y[4], y[5]); w.w = pk2(y[6], y[7]);
;                        ((u32x4*)(hb + (size_t)rr[q] * D) + lane)[64 * j] = w; } }
.LBB0_375:
	s_mov_b64 s[4:5], 0x8400400
	v_cvt_pk_f16_f32 v74, v18, v19
	v_cvt_pk_f16_f32 v75, v20, v21
	v_cvt_pk_f16_f32 v76, v22, v23
	v_cvt_pk_f16_f32 v77, v24, v25
	v_lshl_add_u64 v[78:79], v[132:133], 0, s[4:5]
	global_store_dwordx4 v[68:69], v[74:77], off offset:1024 nt
	s_nop 1
	v_cvt_pk_bf16_f32 v74, v18, v19
	v_cvt_pk_bf16_f32 v75, v20, v21
	v_cvt_pk_bf16_f32 v76, v22, v23
	v_cvt_pk_bf16_f32 v77, v24, v25
	global_store_dwordx4 v[78:79], v[74:77], off
	s_cbranch_execnz .LBB0_374
.LBB0_376:
	global_store_dwordx4 v[130:131], v[18:21], off offset:-2048 nt
	global_store_dwordx4 v[130:131], v[22:25], off offset:-2032 nt
	s_and_b64 vcc, exec, s[36:37]
	s_cbranch_vccnz .LBB0_381
.LBB0_377:
	v_pk_add_f32 v[18:19], v[58:59], v[0:1] op_sel_hi:[1,0] neg_lo:[0,1] neg_hi:[0,1]
	s_and_b64 vcc, exec, s[38:39]
	v_pk_mul_f32 v[18:19], v[18:19], v[72:73] op_sel_hi:[1,0]
	s_mov_b64 s[4:5], -1
	v_pk_fma_f32 v[10:11], v[18:19], v[10:11], v[14:15]
	v_pk_add_f32 v[14:15], v[62:63], v[0:1] op_sel_hi:[1,0] neg_lo:[0,1] neg_hi:[0,1]
	s_nop 0
	v_pk_mul_f32 v[14:15], v[14:15], v[72:73] op_sel_hi:[1,0]
	s_nop 0
	v_pk_fma_f32 v[12:13], v[14:15], v[12:13], v[16:17]
	v_pk_add_f32 v[14:15], v[64:65], v[0:1] op_sel_hi:[1,0] neg_lo:[0,1] neg_hi:[0,1]
	s_nop 0
	v_pk_mul_f32 v[14:15], v[14:15], v[72:73] op_sel_hi:[1,0]
	s_nop 0
	v_pk_fma_f32 v[2:3], v[14:15], v[2:3], v[6:7]
	v_pk_add_f32 v[6:7], v[70:71], v[0:1] op_sel_hi:[1,0] neg_lo:[0,1] neg_hi:[0,1]
	s_nop 0
	v_pk_mul_f32 v[6:7], v[6:7], v[72:73] op_sel_hi:[1,0]
	s_nop 0
	v_pk_fma_f32 v[4:5], v[6:7], v[4:5], v[8:9]
	s_cbranch_vccnz .LBB0_379
	v_cvt_pk_f16_f32 v6, v10, v11
	v_cvt_pk_f16_f32 v7, v12, v13
	v_cvt_pk_f16_f32 v8, v2, v3
	v_cvt_pk_f16_f32 v9, v4, v5
	v_lshl_add_u64 v[14:15], v[106:107], 0, s[58:59]
	global_store_dwordx4 v[14:15], v[6:9], off offset:1024 nt
	s_mov_b64 s[4:5], 0
	s_nop 0
	v_cvt_pk_bf16_f32 v6, v10, v11
	v_cvt_pk_bf16_f32 v7, v12, v13
	v_cvt_pk_bf16_f32 v8, v2, v3
	v_cvt_pk_bf16_f32 v9, v4, v5
	global_store_dwordx4 v[134:135], v[6:9], off offset:1024
.LBB0_379:
	s_andn2_b64 vcc, exec, s[4:5]
	s_cbranch_vccnz .LBB0_381
	s_lshl_b64 s[4:5], s[56:57], 13
	v_lshl_add_u64 v[6:7], v[128:129], 0, s[4:5]
	global_store_dwordx4 v[6:7], v[10:13], off offset:2048 nt
	global_store_dwordx4 v[6:7], v[2:5], off offset:2064 nt

; DI unsigned pk2(float a, float b) { f32x2 v = {a, b}; bf16v2 r = __builtin_convertvector(v, bf16v2); return __builtin_bit_cast(unsigned, r); }
; DI unsigned pkh2(float a, float b) { f32x2 v = {a, b}; h16v2 r = __builtin_convertvector(v, h16v2); return __builtin_bit_cast(unsigned, r); }
; DI void phase_ln(const Params& p, int layer, int gw, int NGW, int lane) {
;     ...
;         for (int j = 0; j < 4; ++j) {
;             const f32x4 g0 = ((const f32x4*)g)[128 * j + 2 * lane], g1 = ((const f32x4*)g)[128 * j + 2 * lane + 1], b0 = ((const f32x4*)b)[128 * j + 2 * lane], b1 = ((const f32x4*)b)[128 * j + 2 * lane + 1];
;             const float gg[8] = {g0[0], g0[1], g0[2], g0[3], g1[0], g1[1], g1[2], g1[3]}, bb[8] = {b0[0], b0[1], b0[2], b0[3], b1[0], b1[1], b1[2], b1[3]};
; #pragma unroll
;             for (int q = 0; q < R; ++q) { if (!ok[q]) continue;
;                 float y[8];
; #pragma unroll
;                 for (int e = 0; e < 8; ++e) y[e] = (v[q][8 * j + e] - mean[q]) * rstd[q] * gg[e] + bb[e];
;                 if (last) { f32x4* o = (f32x4*)(p.out + (size_t)rr[q] * D) + 128 * j + 2 * lane; o[0] = (f32x4){y[0], y[1], y[2], y[3]}; o[1] = (f32x4){y[4], y[5], y[6], y[7]}; }
;                 else { u32x4 hw; hw.x = pkh2(y[0], y[1]); hw.y = pkh2(y[2], y[3]); hw.z = pkh2(y[4], y[5]); hw.w = pkh2(y[6], y[7]);
;                        ((u32x4*)(h16out + (size_t)rr[q] * D) + lane)[64 * j] = hw;
;                        u32x4 w; w.x = pk2(y[0], y[1]); w.y = pk2(y[2], y[3]); w.z = pk2(y[4], y[5]); w.w = pk2(y[6], y[7]);
;                        ((u32x4*)(hb + (size_t)rr[q] * D) + lane)[64 * j] = w; } }
.LBB0_384:
	s_mov_b64 s[4:5], 0x8400800
	v_cvt_pk_f16_f32 v46, v22, v23
	v_cvt_pk_f16_f32 v47, v24, v25
	v_cvt_pk_f16_f32 v48, v18, v19
	v_cvt_pk_f16_f32 v49, v20, v21
	v_lshl_add_u64 v[50:51], v[132:133], 0, s[4:5]
	global_store_dwordx4 v[68:69], v[46:49], off offset:2048 nt
	s_nop 1
	v_cvt_pk_bf16_f32 v46, v22, v23
	v_cvt_pk_bf16_f32 v47, v24, v25
	v_cvt_pk_bf16_f32 v48, v18, v19
	v_cvt_pk_bf16_f32 v49, v20, v21
	global_store_dwordx4 v[50:51], v[46:49], off
	s_cbranch_execnz .LBB0_383
.LBB0_385:
	global_store_dwordx4 v[130:131], v[22:25], off nt
	global_store_dwordx4 v[130:131], v[18:21], off offset:16 nt
	s_and_b64 vcc, exec, s[36:37]
	s_cbranch_vccnz .LBB0_390
.LBB0_386:
	v_pk_add_f32 v[18:19], v[38:39], v[0:1] op_sel_hi:[1,0] neg_lo:[0,1] neg_hi:[0,1]
	s_and_b64 vcc, exec, s[38:39]
	v_pk_mul_f32 v[18:19], v[18:19], v[72:73] op_sel_hi:[1,0]
	s_mov_b64 s[4:5], -1
	v_pk_fma_f32 v[10:11], v[18:19], v[14:15], v[10:11]
	v_pk_add_f32 v[14:15], v[40:41], v[0:1] op_sel_hi:[1,0] neg_lo:[0,1] neg_hi:[0,1]
	s_nop 0
	v_pk_mul_f32 v[14:15], v[14:15], v[72:73] op_sel_hi:[1,0]
	s_nop 0
	v_pk_fma_f32 v[12:13], v[14:15], v[16:17], v[12:13]
	v_pk_add_f32 v[14:15], v[54:55], v[0:1] op_sel_hi:[1,0] neg_lo:[0,1] neg_hi:[0,1]
	s_nop 0
	v_pk_mul_f32 v[14:15], v[14:15], v[72:73] op_sel_hi:[1,0]
	s_nop 0
	v_pk_fma_f32 v[2:3], v[14:15], v[2:3], v[6:7]
	v_pk_add_f32 v[6:7], v[56:57], v[0:1] op_sel_hi:[1,0] neg_lo:[0,1] neg_hi:[0,1]
	s_nop 0
	v_pk_mul_f32 v[6:7], v[6:7], v[72:73] op_sel_hi:[1,0]
	s_nop 0
	v_pk_fma_f32 v[4:5], v[6:7], v[4:5], v[8:9]
	s_cbranch_vccnz .LBB0_388
	v_cvt_pk_f16_f32 v6, v10, v11
	v_cvt_pk_f16_f32 v7, v12, v13
	v_cvt_pk_f16_f32 v8, v2, v3
	v_cvt_pk_f16_f32 v9, v4, v5
	v_lshl_add_u64 v[14:15], v[106:107], 0, s[58:59]
	global_store_dwordx4 v[14:15], v[6:9], off offset:2048 nt
	s_mov_b64 s[4:5], 0
	s_nop 0
	v_cvt_pk_bf16_f32 v6, v10, v11
	v_cvt_pk_bf16_f32 v7, v12, v13
	v_cvt_pk_bf16_f32 v8, v2, v3
	v_cvt_pk_bf16_f32 v9, v4, v5
	global_store_dwordx4 v[134:135], v[6:9], off offset:2048
.LBB0_388:
	s_andn2_b64 vcc, exec, s[4:5]
	s_cbranch_vccnz .LBB0_390
	s_lshl_b64 s[4:5], s[56:57], 13
	s_add_u32 s4, s92, s4
	s_addc_u32 s5, s93, s5
	v_lshl_add_u64 v[6:7], v[104:105], 4, s[4:5]
	v_lshl_add_u64 v[8:9], v[6:7], 0, s[64:65]
	v_add_co_u32_e32 v6, vcc, 0x1000, v6
	s_nop 1
	v_addc_co_u32_e32 v7, vcc, 0, v7, vcc
	global_store_dwordx4 v[6:7], v[10:13], off nt
	global_store_dwordx4 v[8:9], v[2:5], off offset:16 nt

; DI unsigned pk2(float a, float b) { f32x2 v = {a, b}; bf16v2 r = __builtin_convertvector(v, bf16v2); return __builtin_bit_cast(unsigned, r); }
; DI unsigned pkh2(float a, float b) { f32x2 v = {a, b}; h16v2 r = __builtin_convertvector(v, h16v2); return __builtin_bit_cast(unsigned, r); }
; DI void phase_ln(const Params& p, int layer, int gw, int NGW, int lane) {
;     ...
;         for (int j = 0; j < 4; ++j) {
;             const f32x4 g0 = ((const f32x4*)g)[128 * j + 2 * lane], g1 = ((const f32x4*)g)[128 * j + 2 * lane + 1], b0 = ((const f32x4*)b)[128 * j + 2 * lane], b1 = ((const f32x4*)b)[128 * j + 2 * lane + 1];
;             const float gg[8] = {g0[0], g0[1], g0[2], g0[3], g1[0], g1[1], g1[2], g1[3]}, bb[8] = {b0[0], b0[1], b0[2], b0[3], b1[0], b1[1], b1[2], b1[3]};
; #pragma unroll
;             for (int q = 0; q < R; ++q) { if (!ok[q]) continue;
;                 float y[8];
; #pragma unroll
;                 for (int e = 0; e < 8; ++e) y[e] = (v[q][8 * j + e] - mean[q]) * rstd[q] * gg[e] + bb[e];
;                 if (last) { f32x4* o = (f32x4*)(p.out + (size_t)rr[q] * D) + 128 * j + 2 * lane; o[0] = (f32x4){y[0], y[1], y[2], y[3]}; o[1] = (f32x4){y[4], y[5], y[6], y[7]}; }
;                 else { u32x4 hw; hw.x = pkh2(y[0], y[1]); hw.y = pkh2(y[2], y[3]); hw.z = pkh2(y[4], y[5]); hw.w = pkh2(y[6], y[7]);
;                        ((u32x4*)(h16out + (size_t)rr[q] * D) + lane)[64 * j] = hw;
;                        u32x4 w; w.x = pk2(y[0], y[1]); w.y = pk2(y[2], y[3]); w.z = pk2(y[4], y[5]); w.w = pk2(y[6], y[7]);
;                        ((u32x4*)(hb + (size_t)rr[q] * D) + lane)[64 * j] = w; } }
.LBB0_393:
	s_mov_b64 s[4:5], 0x8400c00
	v_cvt_pk_f16_f32 v30, v22, v23
	v_cvt_pk_f16_f32 v31, v24, v25
	v_cvt_pk_f16_f32 v32, v18, v19
	v_cvt_pk_f16_f32 v33, v20, v21
	v_lshl_add_u64 v[38:39], v[132:133], 0, s[4:5]
	global_store_dwordx4 v[68:69], v[30:33], off offset:3072 nt
	s_nop 1
	v_cvt_pk_bf16_f32 v30, v22, v23
	v_cvt_pk_bf16_f32 v31, v24, v25
	v_cvt_pk_bf16_f32 v32, v18, v19
	v_cvt_pk_bf16_f32 v33, v20, v21
	global_store_dwordx4 v[38:39], v[30:33], off
	s_cbranch_execnz .LBB0_392
.LBB0_394:
	global_store_dwordx4 v[130:131], v[22:25], off offset:2048 nt
	global_store_dwordx4 v[130:131], v[18:21], off offset:2064 nt
	s_and_b64 vcc, exec, s[36:37]
	s_cbranch_vccnz .LBB0_356
.LBB0_395:
	v_pk_add_f32 v[18:19], v[34:35], v[0:1] op_sel_hi:[1,0] neg_lo:[0,1] neg_hi:[0,1]
	s_and_b64 vcc, exec, s[38:39]
	v_pk_mul_f32 v[18:19], v[18:19], v[72:73] op_sel_hi:[1,0]
	s_mov_b64 s[4:5], -1
	v_pk_fma_f32 v[10:11], v[18:19], v[14:15], v[10:11]
	v_pk_add_f32 v[14:15], v[26:27], v[0:1] op_sel_hi:[1,0] neg_lo:[0,1] neg_hi:[0,1]
	s_nop 0
	v_pk_mul_f32 v[14:15], v[14:15], v[72:73] op_sel_hi:[1,0]
	s_nop 0
	v_pk_fma_f32 v[12:13], v[14:15], v[16:17], v[12:13]
	v_pk_add_f32 v[14:15], v[36:37], v[0:1] op_sel_hi:[1,0] neg_lo:[0,1] neg_hi:[0,1]
	s_nop 0
	v_pk_mul_f32 v[14:15], v[14:15], v[72:73] op_sel_hi:[1,0]
	s_nop 0
	v_pk_fma_f32 v[2:3], v[14:15], v[2:3], v[6:7]
	v_pk_add_f32 v[6:7], v[28:29], v[0:1] op_sel_hi:[1,0] neg_lo:[0,1] neg_hi:[0,1]
	s_nop 0
	v_pk_mul_f32 v[6:7], v[6:7], v[72:73] op_sel_hi:[1,0]
	s_nop 0
	v_pk_fma_f32 v[4:5], v[6:7], v[4:5], v[8:9]
	s_cbranch_vccnz .LBB0_397
	v_cvt_pk_f16_f32 v6, v10, v11
	v_cvt_pk_f16_f32 v7, v12, v13
	v_cvt_pk_f16_f32 v8, v2, v3
	v_cvt_pk_f16_f32 v9, v4, v5
	v_lshl_add_u64 v[14:15], v[106:107], 0, s[58:59]
	global_store_dwordx4 v[14:15], v[6:9], off offset:3072 nt
	s_mov_b64 s[4:5], 0
	s_nop 0
	v_cvt_pk_bf16_f32 v6, v10, v11
	v_cvt_pk_bf16_f32 v7, v12, v13
	v_cvt_pk_bf16_f32 v8, v2, v3
	v_cvt_pk_bf16_f32 v9, v4, v5
	global_store_dwordx4 v[134:135], v[6:9], off offset:3072
.LBB0_397:
	s_andn2_b64 vcc, exec, s[4:5]
	s_cbranch_vccnz .LBB0_356
	s_lshl_b64 s[4:5], s[56:57], 13
	s_add_u32 s4, s92, s4
	s_addc_u32 s5, s93, s5
	v_lshl_add_u64 v[6:7], v[104:105], 4, s[4:5]
	v_lshl_add_u64 v[8:9], v[6:7], 0, s[68:69]
	v_add_co_u32_e32 v6, vcc, 0x1000, v6
	s_nop 1
	v_addc_co_u32_e32 v7, vcc, 0, v7, vcc
	global_store_dwordx4 v[6:7], v[10:13], off offset:2048 nt
	global_store_dwordx4 v[8:9], v[2:5], off offset:16 nt
	s_branch .LBB0_356
